# gMLP staging: all 8/16 row loads of a pass in flight (was 2-3), same arithmetic; on top of attention QK init + packed SwiGLU epilogue
# speedup vs baseline: 1.0173x; 1.0034x over previous
.LBB0_558:
	s_and_b32 s6, s9, 0xffffff80
	s_ashr_i32 s9, s6, 31
	s_add_u32 s10, s6, s4
	s_addc_u32 s11, s9, 0
	v_lshlrev_b32_e32 v24, 3, v22
	v_lshl_add_u64 v[20:21], s[10:11], 0, v[158:159]
	v_mov_b64_e32 v[22:23], s[2:3]
	v_mad_u64_u32 v[22:23], s[10:11], v20, s90, v[22:23]
	v_mad_i32_i24 v23, v21, s90, v23
	v_lshlrev_b32_e32 v20, 1, v24
	v_mov_b32_e32 v21, v3
	v_lshl_add_u64 v[22:23], s[58:59], 1, v[22:23]
	v_lshl_add_u64 v[28:29], v[22:23], 0, v[20:21]
	v_mov_b32_e32 v20, v28
	v_mov_b32_e32 v21, v29
	v_lshlrev_b32_e32 v159, 7, v158
	v_lshlrev_b32_e32 v24, 5, v158
	v_bitop3_b32 v25, v24, v2, 64 bitop3:0x6c
	v_add3_u32 v44, s77, v25, v159
	v_add_u32_e32 v45, s7, v24
	s_and_b64 vcc, exec, s[12:13]
	s_cbranch_vccnz .Lsgu_single
	v_add_co_u32_e32 v252, vcc, 0x1000, v20
	s_nop 1
	v_addc_co_u32_e32 v253, vcc, 0, v21, vcc
	global_load_dwordx4 v[208:211], v[252:253], off
	v_add_co_u32_e32 v252, vcc, 0xb000, v20
	s_nop 1
	v_addc_co_u32_e32 v253, vcc, 0, v21, vcc
	global_load_dwordx4 v[212:215], v[252:253], off
	v_add_co_u32_e32 v252, vcc, 0x15000, v20
	s_nop 1
	v_addc_co_u32_e32 v253, vcc, 0, v21, vcc
	global_load_dwordx4 v[216:219], v[252:253], off
	v_add_co_u32_e32 v252, vcc, 0x1f000, v20
	s_nop 1
	v_addc_co_u32_e32 v253, vcc, 0, v21, vcc
	global_load_dwordx4 v[220:223], v[252:253], off
	v_add_co_u32_e32 v252, vcc, 0x29000, v20
	s_nop 1
	v_addc_co_u32_e32 v253, vcc, 0, v21, vcc
	global_load_dwordx4 v[224:227], v[252:253], off
	v_add_co_u32_e32 v252, vcc, 0x33000, v20
	s_nop 1
	v_addc_co_u32_e32 v253, vcc, 0, v21, vcc
	global_load_dwordx4 v[228:231], v[252:253], off
	v_add_co_u32_e32 v252, vcc, 0x3d000, v20
	s_nop 1
	v_addc_co_u32_e32 v253, vcc, 0, v21, vcc
	global_load_dwordx4 v[232:235], v[252:253], off
	v_add_co_u32_e32 v252, vcc, 0x47000, v20
	s_nop 1
	v_addc_co_u32_e32 v253, vcc, 0, v21, vcc
	global_load_dwordx4 v[236:239], v[252:253], off
	v_add_co_u32_e32 v252, vcc, 0x51000, v20
	s_nop 1
	v_addc_co_u32_e32 v253, vcc, 0, v21, vcc
	global_load_dwordx4 v[240:243], v[252:253], off
	v_add_co_u32_e32 v252, vcc, 0x5b000, v20
	s_nop 1
	v_addc_co_u32_e32 v253, vcc, 0, v21, vcc
	global_load_dwordx4 v[244:247], v[252:253], off
	v_add_co_u32_e32 v252, vcc, 0x65000, v20
	s_nop 1
	v_addc_co_u32_e32 v253, vcc, 0, v21, vcc
	global_load_dwordx4 v[248:251], v[252:253], off
	v_add_co_u32_e32 v252, vcc, 0x6f000, v20
	s_nop 1
	v_addc_co_u32_e32 v253, vcc, 0, v21, vcc
	global_load_dwordx4 v[32:35], v[252:253], off
	v_add_co_u32_e32 v252, vcc, 0x79000, v20
	s_nop 1
	v_addc_co_u32_e32 v253, vcc, 0, v21, vcc
	global_load_dwordx4 v[36:39], v[252:253], off
	v_add_co_u32_e32 v252, vcc, 0x83000, v20
	s_nop 1
	v_addc_co_u32_e32 v253, vcc, 0, v21, vcc
	global_load_dwordx4 v[40:43], v[252:253], off
	v_add_co_u32_e32 v252, vcc, 0x8d000, v20
	s_nop 1
	v_addc_co_u32_e32 v253, vcc, 0, v21, vcc
	global_load_dwordx4 v[24:27], v[252:253], off
	v_add_co_u32_e32 v252, vcc, 0x97000, v20
	s_nop 1
	v_addc_co_u32_e32 v253, vcc, 0, v21, vcc
	global_load_dwordx4 v[186:189], v[252:253], off
	ds_read_b128 v[28:31], v45
	ds_read_b128 v[168:171], v45 offset:16
	s_waitcnt lgkmcnt(0)
	v_add_f32_e32 v164, v28, v29
	v_add_f32_e32 v165, v168, v169
	v_add_f32_e32 v166, v30, v31
	v_add_f32_e32 v161, v170, v171
	v_add_f32_e32 v164, v164, v166
	v_add_f32_e32 v165, v165, v161
	v_add_f32_e32 v164, v164, v165
	v_fmamk_f32 v164, v164, 0x3b000000, v193
	v_rsq_f32_e32 v164, v164
	s_waitcnt vmcnt(15)
	v_lshlrev_b32_e32 v46, 16, v208
	v_lshlrev_b32_e32 v47, 16, v209
	v_lshlrev_b32_e32 v48, 16, v210
	v_lshlrev_b32_e32 v163, 16, v211
	v_and_b32_e32 v208, 0xffff0000, v208
	v_and_b32_e32 v209, 0xffff0000, v209
	v_and_b32_e32 v210, 0xffff0000, v210
	v_and_b32_e32 v211, 0xffff0000, v211
	v_mul_f32_e32 v208, v164, v208
	v_mul_f32_e32 v209, v164, v209
	v_mul_f32_e32 v210, v164, v210
	v_mul_f32_e32 v211, v164, v211
	v_mul_f32_e32 v46, v164, v46
	v_mul_f32_e32 v47, v164, v47
	v_mul_f32_e32 v48, v164, v48
	v_mul_f32_e32 v163, v164, v163
	v_mul_f32_e32 v208, v9, v208
	v_mul_f32_e32 v209, v11, v209
	v_mul_f32_e32 v210, v5, v210
	v_mul_f32_e32 v211, v7, v211
	v_mul_f32_e32 v46, v8, v46
	v_mul_f32_e32 v47, v10, v47
	v_mul_f32_e32 v48, v4, v48
	v_mul_f32_e32 v163, v6, v163
	v_cvt_pk_bf16_f32 v208, v46, v208
	v_cvt_pk_bf16_f32 v209, v47, v209
	v_cvt_pk_bf16_f32 v210, v48, v210
	v_cvt_pk_bf16_f32 v211, v163, v211
	ds_write_b128 v44, v[208:211]
	ds_read_b128 v[28:31], v45 offset:256
	ds_read_b128 v[168:171], v45 offset:272
	s_waitcnt lgkmcnt(0)
	v_add_f32_e32 v164, v28, v29
	v_add_f32_e32 v165, v168, v169
	v_add_f32_e32 v166, v30, v31
	v_add_f32_e32 v161, v170, v171
	v_add_f32_e32 v164, v164, v166
	v_add_f32_e32 v165, v165, v161
	v_add_f32_e32 v164, v164, v165
	v_fmamk_f32 v164, v164, 0x3b000000, v193
	v_rsq_f32_e32 v164, v164
	s_waitcnt vmcnt(14)
	v_lshlrev_b32_e32 v46, 16, v212
	v_lshlrev_b32_e32 v47, 16, v213
	v_lshlrev_b32_e32 v48, 16, v214
	v_lshlrev_b32_e32 v163, 16, v215
	v_and_b32_e32 v212, 0xffff0000, v212
	v_and_b32_e32 v213, 0xffff0000, v213
	v_and_b32_e32 v214, 0xffff0000, v214
	v_and_b32_e32 v215, 0xffff0000, v215
	v_mul_f32_e32 v212, v164, v212
	v_mul_f32_e32 v213, v164, v213
	v_mul_f32_e32 v214, v164, v214
	v_mul_f32_e32 v215, v164, v215
	v_mul_f32_e32 v46, v164, v46
	v_mul_f32_e32 v47, v164, v47
	v_mul_f32_e32 v48, v164, v48
	v_mul_f32_e32 v163, v164, v163
	v_mul_f32_e32 v212, v9, v212
	v_mul_f32_e32 v213, v11, v213
	v_mul_f32_e32 v214, v5, v214
	v_mul_f32_e32 v215, v7, v215
	v_mul_f32_e32 v46, v8, v46
	v_mul_f32_e32 v47, v10, v47
	v_mul_f32_e32 v48, v4, v48
	v_mul_f32_e32 v163, v6, v163
	v_cvt_pk_bf16_f32 v212, v46, v212
	v_cvt_pk_bf16_f32 v213, v47, v213
	v_cvt_pk_bf16_f32 v214, v48, v214
	v_cvt_pk_bf16_f32 v215, v163, v215
	ds_write_b128 v44, v[212:215] offset:1024
	ds_read_b128 v[28:31], v45 offset:512
	ds_read_b128 v[168:171], v45 offset:528
	s_waitcnt lgkmcnt(0)
	v_add_f32_e32 v164, v28, v29
	v_add_f32_e32 v165, v168, v169
	v_add_f32_e32 v166, v30, v31
	v_add_f32_e32 v161, v170, v171
	v_add_f32_e32 v164, v164, v166
	v_add_f32_e32 v165, v165, v161
	v_add_f32_e32 v164, v164, v165
	v_fmamk_f32 v164, v164, 0x3b000000, v193
	v_rsq_f32_e32 v164, v164
	s_waitcnt vmcnt(13)
	v_lshlrev_b32_e32 v46, 16, v216
	v_lshlrev_b32_e32 v47, 16, v217
	v_lshlrev_b32_e32 v48, 16, v218
	v_lshlrev_b32_e32 v163, 16, v219
	v_and_b32_e32 v216, 0xffff0000, v216
	v_and_b32_e32 v217, 0xffff0000, v217
	v_and_b32_e32 v218, 0xffff0000, v218
	v_and_b32_e32 v219, 0xffff0000, v219
	v_mul_f32_e32 v216, v164, v216
	v_mul_f32_e32 v217, v164, v217
	v_mul_f32_e32 v218, v164, v218
	v_mul_f32_e32 v219, v164, v219
	v_mul_f32_e32 v46, v164, v46
	v_mul_f32_e32 v47, v164, v47
	v_mul_f32_e32 v48, v164, v48
	v_mul_f32_e32 v163, v164, v163
	v_mul_f32_e32 v216, v9, v216
	v_mul_f32_e32 v217, v11, v217
	v_mul_f32_e32 v218, v5, v218
	v_mul_f32_e32 v219, v7, v219
	v_mul_f32_e32 v46, v8, v46
	v_mul_f32_e32 v47, v10, v47
	v_mul_f32_e32 v48, v4, v48
	v_mul_f32_e32 v163, v6, v163
	v_cvt_pk_bf16_f32 v216, v46, v216
	v_cvt_pk_bf16_f32 v217, v47, v217
	v_cvt_pk_bf16_f32 v218, v48, v218
	v_cvt_pk_bf16_f32 v219, v163, v219
	ds_write_b128 v44, v[216:219] offset:2048
	ds_read_b128 v[28:31], v45 offset:768
	ds_read_b128 v[168:171], v45 offset:784
	s_waitcnt lgkmcnt(0)
	v_add_f32_e32 v164, v28, v29
	v_add_f32_e32 v165, v168, v169
	v_add_f32_e32 v166, v30, v31
	v_add_f32_e32 v161, v170, v171
	v_add_f32_e32 v164, v164, v166
	v_add_f32_e32 v165, v165, v161
	v_add_f32_e32 v164, v164, v165
	v_fmamk_f32 v164, v164, 0x3b000000, v193
	v_rsq_f32_e32 v164, v164
	s_waitcnt vmcnt(12)
	v_lshlrev_b32_e32 v46, 16, v220
	v_lshlrev_b32_e32 v47, 16, v221
	v_lshlrev_b32_e32 v48, 16, v222
	v_lshlrev_b32_e32 v163, 16, v223
	v_and_b32_e32 v220, 0xffff0000, v220
	v_and_b32_e32 v221, 0xffff0000, v221
	v_and_b32_e32 v222, 0xffff0000, v222
	v_and_b32_e32 v223, 0xffff0000, v223
	v_mul_f32_e32 v220, v164, v220
	v_mul_f32_e32 v221, v164, v221
	v_mul_f32_e32 v222, v164, v222
	v_mul_f32_e32 v223, v164, v223
	v_mul_f32_e32 v46, v164, v46
	v_mul_f32_e32 v47, v164, v47
	v_mul_f32_e32 v48, v164, v48
	v_mul_f32_e32 v163, v164, v163
	v_mul_f32_e32 v220, v9, v220
	v_mul_f32_e32 v221, v11, v221
	v_mul_f32_e32 v222, v5, v222
	v_mul_f32_e32 v223, v7, v223
	v_mul_f32_e32 v46, v8, v46
	v_mul_f32_e32 v47, v10, v47
	v_mul_f32_e32 v48, v4, v48
	v_mul_f32_e32 v163, v6, v163
	v_cvt_pk_bf16_f32 v220, v46, v220
	v_cvt_pk_bf16_f32 v221, v47, v221
	v_cvt_pk_bf16_f32 v222, v48, v222
	v_cvt_pk_bf16_f32 v223, v163, v223
	ds_write_b128 v44, v[220:223] offset:3072
	ds_read_b128 v[28:31], v45 offset:1024
	ds_read_b128 v[168:171], v45 offset:1040
	s_waitcnt lgkmcnt(0)
	v_add_f32_e32 v164, v28, v29
	v_add_f32_e32 v165, v168, v169
	v_add_f32_e32 v166, v30, v31
	v_add_f32_e32 v161, v170, v171
	v_add_f32_e32 v164, v164, v166
	v_add_f32_e32 v165, v165, v161
	v_add_f32_e32 v164, v164, v165
	v_fmamk_f32 v164, v164, 0x3b000000, v193
	v_rsq_f32_e32 v164, v164
	s_waitcnt vmcnt(11)
	v_lshlrev_b32_e32 v46, 16, v224
	v_lshlrev_b32_e32 v47, 16, v225
	v_lshlrev_b32_e32 v48, 16, v226
	v_lshlrev_b32_e32 v163, 16, v227
	v_and_b32_e32 v224, 0xffff0000, v224
	v_and_b32_e32 v225, 0xffff0000, v225
	v_and_b32_e32 v226, 0xffff0000, v226
	v_and_b32_e32 v227, 0xffff0000, v227
	v_mul_f32_e32 v224, v164, v224
	v_mul_f32_e32 v225, v164, v225
	v_mul_f32_e32 v226, v164, v226
	v_mul_f32_e32 v227, v164, v227
	v_mul_f32_e32 v46, v164, v46
	v_mul_f32_e32 v47, v164, v47
	v_mul_f32_e32 v48, v164, v48
	v_mul_f32_e32 v163, v164, v163
	v_mul_f32_e32 v224, v9, v224
	v_mul_f32_e32 v225, v11, v225
	v_mul_f32_e32 v226, v5, v226
	v_mul_f32_e32 v227, v7, v227
	v_mul_f32_e32 v46, v8, v46
	v_mul_f32_e32 v47, v10, v47
	v_mul_f32_e32 v48, v4, v48
	v_mul_f32_e32 v163, v6, v163
	v_cvt_pk_bf16_f32 v224, v46, v224
	v_cvt_pk_bf16_f32 v225, v47, v225
	v_cvt_pk_bf16_f32 v226, v48, v226
	v_cvt_pk_bf16_f32 v227, v163, v227
	ds_write_b128 v44, v[224:227] offset:4096
	ds_read_b128 v[28:31], v45 offset:1280
	ds_read_b128 v[168:171], v45 offset:1296
	s_waitcnt lgkmcnt(0)
	v_add_f32_e32 v164, v28, v29
	v_add_f32_e32 v165, v168, v169
	v_add_f32_e32 v166, v30, v31
	v_add_f32_e32 v161, v170, v171
	v_add_f32_e32 v164, v164, v166
	v_add_f32_e32 v165, v165, v161
	v_add_f32_e32 v164, v164, v165
	v_fmamk_f32 v164, v164, 0x3b000000, v193
	v_rsq_f32_e32 v164, v164
	s_waitcnt vmcnt(10)
	v_lshlrev_b32_e32 v46, 16, v228
	v_lshlrev_b32_e32 v47, 16, v229
	v_lshlrev_b32_e32 v48, 16, v230
	v_lshlrev_b32_e32 v163, 16, v231
	v_and_b32_e32 v228, 0xffff0000, v228
	v_and_b32_e32 v229, 0xffff0000, v229
	v_and_b32_e32 v230, 0xffff0000, v230
	v_and_b32_e32 v231, 0xffff0000, v231
	v_mul_f32_e32 v228, v164, v228
	v_mul_f32_e32 v229, v164, v229
	v_mul_f32_e32 v230, v164, v230
	v_mul_f32_e32 v231, v164, v231
	v_mul_f32_e32 v46, v164, v46
	v_mul_f32_e32 v47, v164, v47
	v_mul_f32_e32 v48, v164, v48
	v_mul_f32_e32 v163, v164, v163
	v_mul_f32_e32 v228, v9, v228
	v_mul_f32_e32 v229, v11, v229
	v_mul_f32_e32 v230, v5, v230
	v_mul_f32_e32 v231, v7, v231
	v_mul_f32_e32 v46, v8, v46
	v_mul_f32_e32 v47, v10, v47
	v_mul_f32_e32 v48, v4, v48
	v_mul_f32_e32 v163, v6, v163
	v_cvt_pk_bf16_f32 v228, v46, v228
	v_cvt_pk_bf16_f32 v229, v47, v229
	v_cvt_pk_bf16_f32 v230, v48, v230
	v_cvt_pk_bf16_f32 v231, v163, v231
	ds_write_b128 v44, v[228:231] offset:5120
	ds_read_b128 v[28:31], v45 offset:1536
	ds_read_b128 v[168:171], v45 offset:1552
	s_waitcnt lgkmcnt(0)
	v_add_f32_e32 v164, v28, v29
	v_add_f32_e32 v165, v168, v169
	v_add_f32_e32 v166, v30, v31
	v_add_f32_e32 v161, v170, v171
	v_add_f32_e32 v164, v164, v166
	v_add_f32_e32 v165, v165, v161
	v_add_f32_e32 v164, v164, v165
	v_fmamk_f32 v164, v164, 0x3b000000, v193
	v_rsq_f32_e32 v164, v164
	s_waitcnt vmcnt(9)
	v_lshlrev_b32_e32 v46, 16, v232
	v_lshlrev_b32_e32 v47, 16, v233
	v_lshlrev_b32_e32 v48, 16, v234
	v_lshlrev_b32_e32 v163, 16, v235
	v_and_b32_e32 v232, 0xffff0000, v232
	v_and_b32_e32 v233, 0xffff0000, v233
	v_and_b32_e32 v234, 0xffff0000, v234
	v_and_b32_e32 v235, 0xffff0000, v235
	v_mul_f32_e32 v232, v164, v232
	v_mul_f32_e32 v233, v164, v233
	v_mul_f32_e32 v234, v164, v234
	v_mul_f32_e32 v235, v164, v235
	v_mul_f32_e32 v46, v164, v46
	v_mul_f32_e32 v47, v164, v47
	v_mul_f32_e32 v48, v164, v48
	v_mul_f32_e32 v163, v164, v163
	v_mul_f32_e32 v232, v9, v232
	v_mul_f32_e32 v233, v11, v233
	v_mul_f32_e32 v234, v5, v234
	v_mul_f32_e32 v235, v7, v235
	v_mul_f32_e32 v46, v8, v46
	v_mul_f32_e32 v47, v10, v47
	v_mul_f32_e32 v48, v4, v48
	v_mul_f32_e32 v163, v6, v163
	v_cvt_pk_bf16_f32 v232, v46, v232
	v_cvt_pk_bf16_f32 v233, v47, v233
	v_cvt_pk_bf16_f32 v234, v48, v234
	v_cvt_pk_bf16_f32 v235, v163, v235
	ds_write_b128 v44, v[232:235] offset:6144
	ds_read_b128 v[28:31], v45 offset:1792
	ds_read_b128 v[168:171], v45 offset:1808
	s_waitcnt lgkmcnt(0)
	v_add_f32_e32 v164, v28, v29
	v_add_f32_e32 v165, v168, v169
	v_add_f32_e32 v166, v30, v31
	v_add_f32_e32 v161, v170, v171
	v_add_f32_e32 v164, v164, v166
	v_add_f32_e32 v165, v165, v161
	v_add_f32_e32 v164, v164, v165
	v_fmamk_f32 v164, v164, 0x3b000000, v193
	v_rsq_f32_e32 v164, v164
	s_waitcnt vmcnt(8)
	v_lshlrev_b32_e32 v46, 16, v236
	v_lshlrev_b32_e32 v47, 16, v237
	v_lshlrev_b32_e32 v48, 16, v238
	v_lshlrev_b32_e32 v163, 16, v239
	v_and_b32_e32 v236, 0xffff0000, v236
	v_and_b32_e32 v237, 0xffff0000, v237
	v_and_b32_e32 v238, 0xffff0000, v238
	v_and_b32_e32 v239, 0xffff0000, v239
	v_mul_f32_e32 v236, v164, v236
	v_mul_f32_e32 v237, v164, v237
	v_mul_f32_e32 v238, v164, v238
	v_mul_f32_e32 v239, v164, v239
	v_mul_f32_e32 v46, v164, v46
	v_mul_f32_e32 v47, v164, v47
	v_mul_f32_e32 v48, v164, v48
	v_mul_f32_e32 v163, v164, v163
	v_mul_f32_e32 v236, v9, v236
	v_mul_f32_e32 v237, v11, v237
	v_mul_f32_e32 v238, v5, v238
	v_mul_f32_e32 v239, v7, v239
	v_mul_f32_e32 v46, v8, v46
	v_mul_f32_e32 v47, v10, v47
	v_mul_f32_e32 v48, v4, v48
	v_mul_f32_e32 v163, v6, v163
	v_cvt_pk_bf16_f32 v236, v46, v236
	v_cvt_pk_bf16_f32 v237, v47, v237
	v_cvt_pk_bf16_f32 v238, v48, v238
	v_cvt_pk_bf16_f32 v239, v163, v239
	ds_write_b128 v44, v[236:239] offset:7168
	ds_read_b128 v[28:31], v45 offset:2048
	ds_read_b128 v[168:171], v45 offset:2064
	s_waitcnt lgkmcnt(0)
	v_add_f32_e32 v164, v28, v29
	v_add_f32_e32 v165, v168, v169
	v_add_f32_e32 v166, v30, v31
	v_add_f32_e32 v161, v170, v171
	v_add_f32_e32 v164, v164, v166
	v_add_f32_e32 v165, v165, v161
	v_add_f32_e32 v164, v164, v165
	v_fmamk_f32 v164, v164, 0x3b000000, v193
	v_rsq_f32_e32 v164, v164
	s_waitcnt vmcnt(7)
	v_lshlrev_b32_e32 v46, 16, v240
	v_lshlrev_b32_e32 v47, 16, v241
	v_lshlrev_b32_e32 v48, 16, v242
	v_lshlrev_b32_e32 v163, 16, v243
	v_and_b32_e32 v240, 0xffff0000, v240
	v_and_b32_e32 v241, 0xffff0000, v241
	v_and_b32_e32 v242, 0xffff0000, v242
	v_and_b32_e32 v243, 0xffff0000, v243
	v_mul_f32_e32 v240, v164, v240
	v_mul_f32_e32 v241, v164, v241
	v_mul_f32_e32 v242, v164, v242
	v_mul_f32_e32 v243, v164, v243
	v_mul_f32_e32 v46, v164, v46
	v_mul_f32_e32 v47, v164, v47
	v_mul_f32_e32 v48, v164, v48
	v_mul_f32_e32 v163, v164, v163
	v_mul_f32_e32 v240, v9, v240
	v_mul_f32_e32 v241, v11, v241
	v_mul_f32_e32 v242, v5, v242
	v_mul_f32_e32 v243, v7, v243
	v_mul_f32_e32 v46, v8, v46
	v_mul_f32_e32 v47, v10, v47
	v_mul_f32_e32 v48, v4, v48
	v_mul_f32_e32 v163, v6, v163
	v_cvt_pk_bf16_f32 v240, v46, v240
	v_cvt_pk_bf16_f32 v241, v47, v241
	v_cvt_pk_bf16_f32 v242, v48, v242
	v_cvt_pk_bf16_f32 v243, v163, v243
	ds_write_b128 v44, v[240:243] offset:8192
	ds_read_b128 v[28:31], v45 offset:2304
	ds_read_b128 v[168:171], v45 offset:2320
	s_waitcnt lgkmcnt(0)
	v_add_f32_e32 v164, v28, v29
	v_add_f32_e32 v165, v168, v169
	v_add_f32_e32 v166, v30, v31
	v_add_f32_e32 v161, v170, v171
	v_add_f32_e32 v164, v164, v166
	v_add_f32_e32 v165, v165, v161
	v_add_f32_e32 v164, v164, v165
	v_fmamk_f32 v164, v164, 0x3b000000, v193
	v_rsq_f32_e32 v164, v164
	s_waitcnt vmcnt(6)
	v_lshlrev_b32_e32 v46, 16, v244
	v_lshlrev_b32_e32 v47, 16, v245
	v_lshlrev_b32_e32 v48, 16, v246
	v_lshlrev_b32_e32 v163, 16, v247
	v_and_b32_e32 v244, 0xffff0000, v244
	v_and_b32_e32 v245, 0xffff0000, v245
	v_and_b32_e32 v246, 0xffff0000, v246
	v_and_b32_e32 v247, 0xffff0000, v247
	v_mul_f32_e32 v244, v164, v244
	v_mul_f32_e32 v245, v164, v245
	v_mul_f32_e32 v246, v164, v246
	v_mul_f32_e32 v247, v164, v247
	v_mul_f32_e32 v46, v164, v46
	v_mul_f32_e32 v47, v164, v47
	v_mul_f32_e32 v48, v164, v48
	v_mul_f32_e32 v163, v164, v163
	v_mul_f32_e32 v244, v9, v244
	v_mul_f32_e32 v245, v11, v245
	v_mul_f32_e32 v246, v5, v246
	v_mul_f32_e32 v247, v7, v247
	v_mul_f32_e32 v46, v8, v46
	v_mul_f32_e32 v47, v10, v47
	v_mul_f32_e32 v48, v4, v48
	v_mul_f32_e32 v163, v6, v163
	v_cvt_pk_bf16_f32 v244, v46, v244
	v_cvt_pk_bf16_f32 v245, v47, v245
	v_cvt_pk_bf16_f32 v246, v48, v246
	v_cvt_pk_bf16_f32 v247, v163, v247
	ds_write_b128 v44, v[244:247] offset:9216
	ds_read_b128 v[28:31], v45 offset:2560
	ds_read_b128 v[168:171], v45 offset:2576
	s_waitcnt lgkmcnt(0)
	v_add_f32_e32 v164, v28, v29
	v_add_f32_e32 v165, v168, v169
	v_add_f32_e32 v166, v30, v31
	v_add_f32_e32 v161, v170, v171
	v_add_f32_e32 v164, v164, v166
	v_add_f32_e32 v165, v165, v161
	v_add_f32_e32 v164, v164, v165
	v_fmamk_f32 v164, v164, 0x3b000000, v193
	v_rsq_f32_e32 v164, v164
	s_waitcnt vmcnt(5)
	v_lshlrev_b32_e32 v46, 16, v248
	v_lshlrev_b32_e32 v47, 16, v249
	v_lshlrev_b32_e32 v48, 16, v250
	v_lshlrev_b32_e32 v163, 16, v251
	v_and_b32_e32 v248, 0xffff0000, v248
	v_and_b32_e32 v249, 0xffff0000, v249
	v_and_b32_e32 v250, 0xffff0000, v250
	v_and_b32_e32 v251, 0xffff0000, v251
	v_mul_f32_e32 v248, v164, v248
	v_mul_f32_e32 v249, v164, v249
	v_mul_f32_e32 v250, v164, v250
	v_mul_f32_e32 v251, v164, v251
	v_mul_f32_e32 v46, v164, v46
	v_mul_f32_e32 v47, v164, v47
	v_mul_f32_e32 v48, v164, v48
	v_mul_f32_e32 v163, v164, v163
	v_mul_f32_e32 v248, v9, v248
	v_mul_f32_e32 v249, v11, v249
	v_mul_f32_e32 v250, v5, v250
	v_mul_f32_e32 v251, v7, v251
	v_mul_f32_e32 v46, v8, v46
	v_mul_f32_e32 v47, v10, v47
	v_mul_f32_e32 v48, v4, v48
	v_mul_f32_e32 v163, v6, v163
	v_cvt_pk_bf16_f32 v248, v46, v248
	v_cvt_pk_bf16_f32 v249, v47, v249
	v_cvt_pk_bf16_f32 v250, v48, v250
	v_cvt_pk_bf16_f32 v251, v163, v251
	ds_write_b128 v44, v[248:251] offset:10240
	ds_read_b128 v[28:31], v45 offset:2816
	ds_read_b128 v[168:171], v45 offset:2832
	s_waitcnt lgkmcnt(0)
	v_add_f32_e32 v164, v28, v29
	v_add_f32_e32 v165, v168, v169
	v_add_f32_e32 v166, v30, v31
	v_add_f32_e32 v161, v170, v171
	v_add_f32_e32 v164, v164, v166
	v_add_f32_e32 v165, v165, v161
	v_add_f32_e32 v164, v164, v165
	v_fmamk_f32 v164, v164, 0x3b000000, v193
	v_rsq_f32_e32 v164, v164
	s_waitcnt vmcnt(4)
	v_lshlrev_b32_e32 v46, 16, v32
	v_lshlrev_b32_e32 v47, 16, v33
	v_lshlrev_b32_e32 v48, 16, v34
	v_lshlrev_b32_e32 v163, 16, v35
	v_and_b32_e32 v32, 0xffff0000, v32
	v_and_b32_e32 v33, 0xffff0000, v33
	v_and_b32_e32 v34, 0xffff0000, v34
	v_and_b32_e32 v35, 0xffff0000, v35
	v_mul_f32_e32 v32, v164, v32
	v_mul_f32_e32 v33, v164, v33
	v_mul_f32_e32 v34, v164, v34
	v_mul_f32_e32 v35, v164, v35
	v_mul_f32_e32 v46, v164, v46
	v_mul_f32_e32 v47, v164, v47
	v_mul_f32_e32 v48, v164, v48
	v_mul_f32_e32 v163, v164, v163
	v_mul_f32_e32 v32, v9, v32
	v_mul_f32_e32 v33, v11, v33
	v_mul_f32_e32 v34, v5, v34
	v_mul_f32_e32 v35, v7, v35
	v_mul_f32_e32 v46, v8, v46
	v_mul_f32_e32 v47, v10, v47
	v_mul_f32_e32 v48, v4, v48
	v_mul_f32_e32 v163, v6, v163
	v_cvt_pk_bf16_f32 v32, v46, v32
	v_cvt_pk_bf16_f32 v33, v47, v33
	v_cvt_pk_bf16_f32 v34, v48, v34
	v_cvt_pk_bf16_f32 v35, v163, v35
	ds_write_b128 v44, v[32:35] offset:11264
	ds_read_b128 v[28:31], v45 offset:3072
	ds_read_b128 v[168:171], v45 offset:3088
	s_waitcnt lgkmcnt(0)
	v_add_f32_e32 v164, v28, v29
	v_add_f32_e32 v165, v168, v169
	v_add_f32_e32 v166, v30, v31
	v_add_f32_e32 v161, v170, v171
	v_add_f32_e32 v164, v164, v166
	v_add_f32_e32 v165, v165, v161
	v_add_f32_e32 v164, v164, v165
	v_fmamk_f32 v164, v164, 0x3b000000, v193
	v_rsq_f32_e32 v164, v164
	s_waitcnt vmcnt(3)
	v_lshlrev_b32_e32 v46, 16, v36
	v_lshlrev_b32_e32 v47, 16, v37
	v_lshlrev_b32_e32 v48, 16, v38
	v_lshlrev_b32_e32 v163, 16, v39
	v_and_b32_e32 v36, 0xffff0000, v36
	v_and_b32_e32 v37, 0xffff0000, v37
	v_and_b32_e32 v38, 0xffff0000, v38
	v_and_b32_e32 v39, 0xffff0000, v39
	v_mul_f32_e32 v36, v164, v36
	v_mul_f32_e32 v37, v164, v37
	v_mul_f32_e32 v38, v164, v38
	v_mul_f32_e32 v39, v164, v39
	v_mul_f32_e32 v46, v164, v46
	v_mul_f32_e32 v47, v164, v47
	v_mul_f32_e32 v48, v164, v48
	v_mul_f32_e32 v163, v164, v163
	v_mul_f32_e32 v36, v9, v36
	v_mul_f32_e32 v37, v11, v37
	v_mul_f32_e32 v38, v5, v38
	v_mul_f32_e32 v39, v7, v39
	v_mul_f32_e32 v46, v8, v46
	v_mul_f32_e32 v47, v10, v47
	v_mul_f32_e32 v48, v4, v48
	v_mul_f32_e32 v163, v6, v163
	v_cvt_pk_bf16_f32 v36, v46, v36
	v_cvt_pk_bf16_f32 v37, v47, v37
	v_cvt_pk_bf16_f32 v38, v48, v38
	v_cvt_pk_bf16_f32 v39, v163, v39
	ds_write_b128 v44, v[36:39] offset:12288
	ds_read_b128 v[28:31], v45 offset:3328
	ds_read_b128 v[168:171], v45 offset:3344
	s_waitcnt lgkmcnt(0)
	v_add_f32_e32 v164, v28, v29
	v_add_f32_e32 v165, v168, v169
	v_add_f32_e32 v166, v30, v31
	v_add_f32_e32 v161, v170, v171
	v_add_f32_e32 v164, v164, v166
	v_add_f32_e32 v165, v165, v161
	v_add_f32_e32 v164, v164, v165
	v_fmamk_f32 v164, v164, 0x3b000000, v193
	v_rsq_f32_e32 v164, v164
	s_waitcnt vmcnt(2)
	v_lshlrev_b32_e32 v46, 16, v40
	v_lshlrev_b32_e32 v47, 16, v41
	v_lshlrev_b32_e32 v48, 16, v42
	v_lshlrev_b32_e32 v163, 16, v43
	v_and_b32_e32 v40, 0xffff0000, v40
	v_and_b32_e32 v41, 0xffff0000, v41
	v_and_b32_e32 v42, 0xffff0000, v42
	v_and_b32_e32 v43, 0xffff0000, v43
	v_mul_f32_e32 v40, v164, v40
	v_mul_f32_e32 v41, v164, v41
	v_mul_f32_e32 v42, v164, v42
	v_mul_f32_e32 v43, v164, v43
	v_mul_f32_e32 v46, v164, v46
	v_mul_f32_e32 v47, v164, v47
	v_mul_f32_e32 v48, v164, v48
	v_mul_f32_e32 v163, v164, v163
	v_mul_f32_e32 v40, v9, v40
	v_mul_f32_e32 v41, v11, v41
	v_mul_f32_e32 v42, v5, v42
	v_mul_f32_e32 v43, v7, v43
	v_mul_f32_e32 v46, v8, v46
	v_mul_f32_e32 v47, v10, v47
	v_mul_f32_e32 v48, v4, v48
	v_mul_f32_e32 v163, v6, v163
	v_cvt_pk_bf16_f32 v40, v46, v40
	v_cvt_pk_bf16_f32 v41, v47, v41
	v_cvt_pk_bf16_f32 v42, v48, v42
	v_cvt_pk_bf16_f32 v43, v163, v43
	ds_write_b128 v44, v[40:43] offset:13312
	ds_read_b128 v[28:31], v45 offset:3584
	ds_read_b128 v[168:171], v45 offset:3600
	s_waitcnt lgkmcnt(0)
	v_add_f32_e32 v164, v28, v29
	v_add_f32_e32 v165, v168, v169
	v_add_f32_e32 v166, v30, v31
	v_add_f32_e32 v161, v170, v171
	v_add_f32_e32 v164, v164, v166
	v_add_f32_e32 v165, v165, v161
	v_add_f32_e32 v164, v164, v165
	v_fmamk_f32 v164, v164, 0x3b000000, v193
	v_rsq_f32_e32 v164, v164
	s_waitcnt vmcnt(1)
	v_lshlrev_b32_e32 v46, 16, v24
	v_lshlrev_b32_e32 v47, 16, v25
	v_lshlrev_b32_e32 v48, 16, v26
	v_lshlrev_b32_e32 v163, 16, v27
	v_and_b32_e32 v24, 0xffff0000, v24
	v_and_b32_e32 v25, 0xffff0000, v25
	v_and_b32_e32 v26, 0xffff0000, v26
	v_and_b32_e32 v27, 0xffff0000, v27
	v_mul_f32_e32 v24, v164, v24
	v_mul_f32_e32 v25, v164, v25
	v_mul_f32_e32 v26, v164, v26
	v_mul_f32_e32 v27, v164, v27
	v_mul_f32_e32 v46, v164, v46
	v_mul_f32_e32 v47, v164, v47
	v_mul_f32_e32 v48, v164, v48
	v_mul_f32_e32 v163, v164, v163
	v_mul_f32_e32 v24, v9, v24
	v_mul_f32_e32 v25, v11, v25
	v_mul_f32_e32 v26, v5, v26
	v_mul_f32_e32 v27, v7, v27
	v_mul_f32_e32 v46, v8, v46
	v_mul_f32_e32 v47, v10, v47
	v_mul_f32_e32 v48, v4, v48
	v_mul_f32_e32 v163, v6, v163
	v_cvt_pk_bf16_f32 v24, v46, v24
	v_cvt_pk_bf16_f32 v25, v47, v25
	v_cvt_pk_bf16_f32 v26, v48, v26
	v_cvt_pk_bf16_f32 v27, v163, v27
	ds_write_b128 v44, v[24:27] offset:14336
	ds_read_b128 v[28:31], v45 offset:3840
	ds_read_b128 v[168:171], v45 offset:3856
	s_waitcnt lgkmcnt(0)
	v_add_f32_e32 v164, v28, v29
	v_add_f32_e32 v165, v168, v169
	v_add_f32_e32 v166, v30, v31
	v_add_f32_e32 v161, v170, v171
	v_add_f32_e32 v164, v164, v166
	v_add_f32_e32 v165, v165, v161
	v_add_f32_e32 v164, v164, v165
	v_fmamk_f32 v164, v164, 0x3b000000, v193
	v_rsq_f32_e32 v164, v164
	s_waitcnt vmcnt(0)
	v_lshlrev_b32_e32 v46, 16, v186
	v_lshlrev_b32_e32 v47, 16, v187
	v_lshlrev_b32_e32 v48, 16, v188
	v_lshlrev_b32_e32 v163, 16, v189
	v_and_b32_e32 v186, 0xffff0000, v186
	v_and_b32_e32 v187, 0xffff0000, v187
	v_and_b32_e32 v188, 0xffff0000, v188
	v_and_b32_e32 v189, 0xffff0000, v189
	v_mul_f32_e32 v186, v164, v186
	v_mul_f32_e32 v187, v164, v187
	v_mul_f32_e32 v188, v164, v188
	v_mul_f32_e32 v189, v164, v189
	v_mul_f32_e32 v46, v164, v46
	v_mul_f32_e32 v47, v164, v47
	v_mul_f32_e32 v48, v164, v48
	v_mul_f32_e32 v163, v164, v163
	v_mul_f32_e32 v186, v9, v186
	v_mul_f32_e32 v187, v11, v187
	v_mul_f32_e32 v188, v5, v188
	v_mul_f32_e32 v189, v7, v189
	v_mul_f32_e32 v46, v8, v46
	v_mul_f32_e32 v47, v10, v47
	v_mul_f32_e32 v48, v4, v48
	v_mul_f32_e32 v163, v6, v163
	v_cvt_pk_bf16_f32 v186, v46, v186
	v_cvt_pk_bf16_f32 v187, v47, v187
	v_cvt_pk_bf16_f32 v188, v48, v188
	v_cvt_pk_bf16_f32 v189, v163, v189
	ds_write_b128 v44, v[186:189] offset:15360
	s_branch .LBB0_560
.Lsgu_single:
	v_add_co_u32_e32 v252, vcc, 0x1000, v20
	s_nop 1
	v_addc_co_u32_e32 v253, vcc, 0, v21, vcc
	global_load_dwordx4 v[208:211], v[252:253], off
	v_add_co_u32_e32 v252, vcc, 0xb000, v20
	s_nop 1
	v_addc_co_u32_e32 v253, vcc, 0, v21, vcc
	global_load_dwordx4 v[212:215], v[252:253], off
	v_add_co_u32_e32 v252, vcc, 0x15000, v20
	s_nop 1
	v_addc_co_u32_e32 v253, vcc, 0, v21, vcc
	global_load_dwordx4 v[216:219], v[252:253], off
	v_add_co_u32_e32 v252, vcc, 0x1f000, v20
	s_nop 1
	v_addc_co_u32_e32 v253, vcc, 0, v21, vcc
	global_load_dwordx4 v[220:223], v[252:253], off
	v_add_co_u32_e32 v252, vcc, 0x29000, v20
	s_nop 1
	v_addc_co_u32_e32 v253, vcc, 0, v21, vcc
	global_load_dwordx4 v[224:227], v[252:253], off
	v_add_co_u32_e32 v252, vcc, 0x33000, v20
	s_nop 1
	v_addc_co_u32_e32 v253, vcc, 0, v21, vcc
	global_load_dwordx4 v[228:231], v[252:253], off
	v_add_co_u32_e32 v252, vcc, 0x3d000, v20
	s_nop 1
	v_addc_co_u32_e32 v253, vcc, 0, v21, vcc
	global_load_dwordx4 v[232:235], v[252:253], off
	v_add_co_u32_e32 v252, vcc, 0x47000, v20
	s_nop 1
	v_addc_co_u32_e32 v253, vcc, 0, v21, vcc
	global_load_dwordx4 v[236:239], v[252:253], off
	ds_read_b128 v[28:31], v45
	ds_read_b128 v[168:171], v45 offset:16
	s_waitcnt lgkmcnt(0)
	v_add_f32_e32 v164, v28, v29
	v_add_f32_e32 v165, v168, v169
	v_add_f32_e32 v166, v30, v31
	v_add_f32_e32 v161, v170, v171
	v_add_f32_e32 v164, v164, v166
	v_add_f32_e32 v165, v165, v161
	v_add_f32_e32 v164, v164, v165
	v_fmamk_f32 v164, v164, 0x3b000000, v193
	v_rsq_f32_e32 v164, v164
	s_waitcnt vmcnt(7)
	v_lshlrev_b32_e32 v46, 16, v208
	v_lshlrev_b32_e32 v47, 16, v209
	v_lshlrev_b32_e32 v48, 16, v210
	v_lshlrev_b32_e32 v163, 16, v211
	v_and_b32_e32 v208, 0xffff0000, v208
	v_and_b32_e32 v209, 0xffff0000, v209
	v_and_b32_e32 v210, 0xffff0000, v210
	v_and_b32_e32 v211, 0xffff0000, v211
	v_mul_f32_e32 v208, v164, v208
	v_mul_f32_e32 v209, v164, v209
	v_mul_f32_e32 v210, v164, v210
	v_mul_f32_e32 v211, v164, v211
	v_mul_f32_e32 v46, v164, v46
	v_mul_f32_e32 v47, v164, v47
	v_mul_f32_e32 v48, v164, v48
	v_mul_f32_e32 v163, v164, v163
	v_mul_f32_e32 v208, v9, v208
	v_mul_f32_e32 v209, v11, v209
	v_mul_f32_e32 v210, v5, v210
	v_mul_f32_e32 v211, v7, v211
	v_mul_f32_e32 v46, v8, v46
	v_mul_f32_e32 v47, v10, v47
	v_mul_f32_e32 v48, v4, v48
	v_mul_f32_e32 v163, v6, v163
	v_cvt_pk_bf16_f32 v208, v46, v208
	v_cvt_pk_bf16_f32 v209, v47, v209
	v_cvt_pk_bf16_f32 v210, v48, v210
	v_cvt_pk_bf16_f32 v211, v163, v211
	ds_write_b128 v44, v[208:211]
	ds_read_b128 v[28:31], v45 offset:256
	ds_read_b128 v[168:171], v45 offset:272
	s_waitcnt lgkmcnt(0)
	v_add_f32_e32 v164, v28, v29
	v_add_f32_e32 v165, v168, v169
	v_add_f32_e32 v166, v30, v31
	v_add_f32_e32 v161, v170, v171
	v_add_f32_e32 v164, v164, v166
	v_add_f32_e32 v165, v165, v161
	v_add_f32_e32 v164, v164, v165
	v_fmamk_f32 v164, v164, 0x3b000000, v193
	v_rsq_f32_e32 v164, v164
	s_waitcnt vmcnt(6)
	v_lshlrev_b32_e32 v46, 16, v212
	v_lshlrev_b32_e32 v47, 16, v213
	v_lshlrev_b32_e32 v48, 16, v214
	v_lshlrev_b32_e32 v163, 16, v215
	v_and_b32_e32 v212, 0xffff0000, v212
	v_and_b32_e32 v213, 0xffff0000, v213
	v_and_b32_e32 v214, 0xffff0000, v214
	v_and_b32_e32 v215, 0xffff0000, v215
	v_mul_f32_e32 v212, v164, v212
	v_mul_f32_e32 v213, v164, v213
	v_mul_f32_e32 v214, v164, v214
	v_mul_f32_e32 v215, v164, v215
	v_mul_f32_e32 v46, v164, v46
	v_mul_f32_e32 v47, v164, v47
	v_mul_f32_e32 v48, v164, v48
	v_mul_f32_e32 v163, v164, v163
	v_mul_f32_e32 v212, v9, v212
	v_mul_f32_e32 v213, v11, v213
	v_mul_f32_e32 v214, v5, v214
	v_mul_f32_e32 v215, v7, v215
	v_mul_f32_e32 v46, v8, v46
	v_mul_f32_e32 v47, v10, v47
	v_mul_f32_e32 v48, v4, v48
	v_mul_f32_e32 v163, v6, v163
	v_cvt_pk_bf16_f32 v212, v46, v212
	v_cvt_pk_bf16_f32 v213, v47, v213
	v_cvt_pk_bf16_f32 v214, v48, v214
	v_cvt_pk_bf16_f32 v215, v163, v215
	ds_write_b128 v44, v[212:215] offset:1024
	ds_read_b128 v[28:31], v45 offset:512
	ds_read_b128 v[168:171], v45 offset:528
	s_waitcnt lgkmcnt(0)
	v_add_f32_e32 v164, v28, v29
	v_add_f32_e32 v165, v168, v169
	v_add_f32_e32 v166, v30, v31
	v_add_f32_e32 v161, v170, v171
	v_add_f32_e32 v164, v164, v166
	v_add_f32_e32 v165, v165, v161
	v_add_f32_e32 v164, v164, v165
	v_fmamk_f32 v164, v164, 0x3b000000, v193
	v_rsq_f32_e32 v164, v164
	s_waitcnt vmcnt(5)
	v_lshlrev_b32_e32 v46, 16, v216
	v_lshlrev_b32_e32 v47, 16, v217
	v_lshlrev_b32_e32 v48, 16, v218
	v_lshlrev_b32_e32 v163, 16, v219
	v_and_b32_e32 v216, 0xffff0000, v216
	v_and_b32_e32 v217, 0xffff0000, v217
	v_and_b32_e32 v218, 0xffff0000, v218
	v_and_b32_e32 v219, 0xffff0000, v219
	v_mul_f32_e32 v216, v164, v216
	v_mul_f32_e32 v217, v164, v217
	v_mul_f32_e32 v218, v164, v218
	v_mul_f32_e32 v219, v164, v219
	v_mul_f32_e32 v46, v164, v46
	v_mul_f32_e32 v47, v164, v47
	v_mul_f32_e32 v48, v164, v48
	v_mul_f32_e32 v163, v164, v163
	v_mul_f32_e32 v216, v9, v216
	v_mul_f32_e32 v217, v11, v217
	v_mul_f32_e32 v218, v5, v218
	v_mul_f32_e32 v219, v7, v219
	v_mul_f32_e32 v46, v8, v46
	v_mul_f32_e32 v47, v10, v47
	v_mul_f32_e32 v48, v4, v48
	v_mul_f32_e32 v163, v6, v163
	v_cvt_pk_bf16_f32 v216, v46, v216
	v_cvt_pk_bf16_f32 v217, v47, v217
	v_cvt_pk_bf16_f32 v218, v48, v218
	v_cvt_pk_bf16_f32 v219, v163, v219
	ds_write_b128 v44, v[216:219] offset:2048
	ds_read_b128 v[28:31], v45 offset:768
	ds_read_b128 v[168:171], v45 offset:784
	s_waitcnt lgkmcnt(0)
	v_add_f32_e32 v164, v28, v29
	v_add_f32_e32 v165, v168, v169
	v_add_f32_e32 v166, v30, v31
	v_add_f32_e32 v161, v170, v171
	v_add_f32_e32 v164, v164, v166
	v_add_f32_e32 v165, v165, v161
	v_add_f32_e32 v164, v164, v165
	v_fmamk_f32 v164, v164, 0x3b000000, v193
	v_rsq_f32_e32 v164, v164
	s_waitcnt vmcnt(4)
	v_lshlrev_b32_e32 v46, 16, v220
	v_lshlrev_b32_e32 v47, 16, v221
	v_lshlrev_b32_e32 v48, 16, v222
	v_lshlrev_b32_e32 v163, 16, v223
	v_and_b32_e32 v220, 0xffff0000, v220
	v_and_b32_e32 v221, 0xffff0000, v221
	v_and_b32_e32 v222, 0xffff0000, v222
	v_and_b32_e32 v223, 0xffff0000, v223
	v_mul_f32_e32 v220, v164, v220
	v_mul_f32_e32 v221, v164, v221
	v_mul_f32_e32 v222, v164, v222
	v_mul_f32_e32 v223, v164, v223
	v_mul_f32_e32 v46, v164, v46
	v_mul_f32_e32 v47, v164, v47
	v_mul_f32_e32 v48, v164, v48
	v_mul_f32_e32 v163, v164, v163
	v_mul_f32_e32 v220, v9, v220
	v_mul_f32_e32 v221, v11, v221
	v_mul_f32_e32 v222, v5, v222
	v_mul_f32_e32 v223, v7, v223
	v_mul_f32_e32 v46, v8, v46
	v_mul_f32_e32 v47, v10, v47
	v_mul_f32_e32 v48, v4, v48
	v_mul_f32_e32 v163, v6, v163
	v_cvt_pk_bf16_f32 v220, v46, v220
	v_cvt_pk_bf16_f32 v221, v47, v221
	v_cvt_pk_bf16_f32 v222, v48, v222
	v_cvt_pk_bf16_f32 v223, v163, v223
	ds_write_b128 v44, v[220:223] offset:3072
	ds_read_b128 v[28:31], v45 offset:1024
	ds_read_b128 v[168:171], v45 offset:1040
	s_waitcnt lgkmcnt(0)
	v_add_f32_e32 v164, v28, v29
	v_add_f32_e32 v165, v168, v169
	v_add_f32_e32 v166, v30, v31
	v_add_f32_e32 v161, v170, v171
	v_add_f32_e32 v164, v164, v166
	v_add_f32_e32 v165, v165, v161
	v_add_f32_e32 v164, v164, v165
	v_fmamk_f32 v164, v164, 0x3b000000, v193
	v_rsq_f32_e32 v164, v164
	s_waitcnt vmcnt(3)
	v_lshlrev_b32_e32 v46, 16, v224
	v_lshlrev_b32_e32 v47, 16, v225
	v_lshlrev_b32_e32 v48, 16, v226
	v_lshlrev_b32_e32 v163, 16, v227
	v_and_b32_e32 v224, 0xffff0000, v224
	v_and_b32_e32 v225, 0xffff0000, v225
	v_and_b32_e32 v226, 0xffff0000, v226
	v_and_b32_e32 v227, 0xffff0000, v227
	v_mul_f32_e32 v224, v164, v224
	v_mul_f32_e32 v225, v164, v225
	v_mul_f32_e32 v226, v164, v226
	v_mul_f32_e32 v227, v164, v227
	v_mul_f32_e32 v46, v164, v46
	v_mul_f32_e32 v47, v164, v47
	v_mul_f32_e32 v48, v164, v48
	v_mul_f32_e32 v163, v164, v163
	v_mul_f32_e32 v224, v9, v224
	v_mul_f32_e32 v225, v11, v225
	v_mul_f32_e32 v226, v5, v226
	v_mul_f32_e32 v227, v7, v227
	v_mul_f32_e32 v46, v8, v46
	v_mul_f32_e32 v47, v10, v47
	v_mul_f32_e32 v48, v4, v48
	v_mul_f32_e32 v163, v6, v163
	v_cvt_pk_bf16_f32 v224, v46, v224
	v_cvt_pk_bf16_f32 v225, v47, v225
	v_cvt_pk_bf16_f32 v226, v48, v226
	v_cvt_pk_bf16_f32 v227, v163, v227
	ds_write_b128 v44, v[224:227] offset:4096
	ds_read_b128 v[28:31], v45 offset:1280
	ds_read_b128 v[168:171], v45 offset:1296
	s_waitcnt lgkmcnt(0)
	v_add_f32_e32 v164, v28, v29
	v_add_f32_e32 v165, v168, v169
	v_add_f32_e32 v166, v30, v31
	v_add_f32_e32 v161, v170, v171
	v_add_f32_e32 v164, v164, v166
	v_add_f32_e32 v165, v165, v161
	v_add_f32_e32 v164, v164, v165
	v_fmamk_f32 v164, v164, 0x3b000000, v193
	v_rsq_f32_e32 v164, v164
	s_waitcnt vmcnt(2)
	v_lshlrev_b32_e32 v46, 16, v228
	v_lshlrev_b32_e32 v47, 16, v229
	v_lshlrev_b32_e32 v48, 16, v230
	v_lshlrev_b32_e32 v163, 16, v231
	v_and_b32_e32 v228, 0xffff0000, v228
	v_and_b32_e32 v229, 0xffff0000, v229
	v_and_b32_e32 v230, 0xffff0000, v230
	v_and_b32_e32 v231, 0xffff0000, v231
	v_mul_f32_e32 v228, v164, v228
	v_mul_f32_e32 v229, v164, v229
	v_mul_f32_e32 v230, v164, v230
	v_mul_f32_e32 v231, v164, v231
	v_mul_f32_e32 v46, v164, v46
	v_mul_f32_e32 v47, v164, v47
	v_mul_f32_e32 v48, v164, v48
	v_mul_f32_e32 v163, v164, v163
	v_mul_f32_e32 v228, v9, v228
	v_mul_f32_e32 v229, v11, v229
	v_mul_f32_e32 v230, v5, v230
	v_mul_f32_e32 v231, v7, v231
	v_mul_f32_e32 v46, v8, v46
	v_mul_f32_e32 v47, v10, v47
	v_mul_f32_e32 v48, v4, v48
	v_mul_f32_e32 v163, v6, v163
	v_cvt_pk_bf16_f32 v228, v46, v228
	v_cvt_pk_bf16_f32 v229, v47, v229
	v_cvt_pk_bf16_f32 v230, v48, v230
	v_cvt_pk_bf16_f32 v231, v163, v231
	ds_write_b128 v44, v[228:231] offset:5120
	ds_read_b128 v[28:31], v45 offset:1536
	ds_read_b128 v[168:171], v45 offset:1552
	s_waitcnt lgkmcnt(0)
	v_add_f32_e32 v164, v28, v29
	v_add_f32_e32 v165, v168, v169
	v_add_f32_e32 v166, v30, v31
	v_add_f32_e32 v161, v170, v171
	v_add_f32_e32 v164, v164, v166
	v_add_f32_e32 v165, v165, v161
	v_add_f32_e32 v164, v164, v165
	v_fmamk_f32 v164, v164, 0x3b000000, v193
	v_rsq_f32_e32 v164, v164
	s_waitcnt vmcnt(1)
	v_lshlrev_b32_e32 v46, 16, v232
	v_lshlrev_b32_e32 v47, 16, v233
	v_lshlrev_b32_e32 v48, 16, v234
	v_lshlrev_b32_e32 v163, 16, v235
	v_and_b32_e32 v232, 0xffff0000, v232
	v_and_b32_e32 v233, 0xffff0000, v233
	v_and_b32_e32 v234, 0xffff0000, v234
	v_and_b32_e32 v235, 0xffff0000, v235
	v_mul_f32_e32 v232, v164, v232
	v_mul_f32_e32 v233, v164, v233
	v_mul_f32_e32 v234, v164, v234
	v_mul_f32_e32 v235, v164, v235
	v_mul_f32_e32 v46, v164, v46
	v_mul_f32_e32 v47, v164, v47
	v_mul_f32_e32 v48, v164, v48
	v_mul_f32_e32 v163, v164, v163
	v_mul_f32_e32 v232, v9, v232
	v_mul_f32_e32 v233, v11, v233
	v_mul_f32_e32 v234, v5, v234
	v_mul_f32_e32 v235, v7, v235
	v_mul_f32_e32 v46, v8, v46
	v_mul_f32_e32 v47, v10, v47
	v_mul_f32_e32 v48, v4, v48
	v_mul_f32_e32 v163, v6, v163
	v_cvt_pk_bf16_f32 v232, v46, v232
	v_cvt_pk_bf16_f32 v233, v47, v233
	v_cvt_pk_bf16_f32 v234, v48, v234
	v_cvt_pk_bf16_f32 v235, v163, v235
	ds_write_b128 v44, v[232:235] offset:6144
	ds_read_b128 v[28:31], v45 offset:1792
	ds_read_b128 v[168:171], v45 offset:1808
	s_waitcnt lgkmcnt(0)
	v_add_f32_e32 v164, v28, v29
	v_add_f32_e32 v165, v168, v169
	v_add_f32_e32 v166, v30, v31
	v_add_f32_e32 v161, v170, v171
	v_add_f32_e32 v164, v164, v166
	v_add_f32_e32 v165, v165, v161
	v_add_f32_e32 v164, v164, v165
	v_fmamk_f32 v164, v164, 0x3b000000, v193
	v_rsq_f32_e32 v164, v164
	s_waitcnt vmcnt(0)
	v_lshlrev_b32_e32 v46, 16, v236
	v_lshlrev_b32_e32 v47, 16, v237
	v_lshlrev_b32_e32 v48, 16, v238
	v_lshlrev_b32_e32 v163, 16, v239
	v_and_b32_e32 v236, 0xffff0000, v236
	v_and_b32_e32 v237, 0xffff0000, v237
	v_and_b32_e32 v238, 0xffff0000, v238
	v_and_b32_e32 v239, 0xffff0000, v239
	v_mul_f32_e32 v236, v164, v236
	v_mul_f32_e32 v237, v164, v237
	v_mul_f32_e32 v238, v164, v238
	v_mul_f32_e32 v239, v164, v239
	v_mul_f32_e32 v46, v164, v46
	v_mul_f32_e32 v47, v164, v47
	v_mul_f32_e32 v48, v164, v48
	v_mul_f32_e32 v163, v164, v163
	v_mul_f32_e32 v236, v9, v236
	v_mul_f32_e32 v237, v11, v237
	v_mul_f32_e32 v238, v5, v238
	v_mul_f32_e32 v239, v7, v239
	v_mul_f32_e32 v46, v8, v46
	v_mul_f32_e32 v47, v10, v47
	v_mul_f32_e32 v48, v4, v48
	v_mul_f32_e32 v163, v6, v163
	v_cvt_pk_bf16_f32 v236, v46, v236
	v_cvt_pk_bf16_f32 v237, v47, v237
	v_cvt_pk_bf16_f32 v238, v48, v238
	v_cvt_pk_bf16_f32 v239, v163, v239
	ds_write_b128 v44, v[236:239] offset:7168
